# GEMM1 epilogue stores sc1 nt (write-through plus non-temporal) instead of sc1 only
# speedup vs baseline: 1.0140x; 1.0039x over previous
; __device__ __forceinline__ unsigned cvt_pk_bf16(float lo, float hi) { unsigned r; asm volatile("v_cvt_pk_bf16_f32 %0, %1, %2" : "=v"(r) : "v"(lo), "v"(hi)); return r; }
; __device__ __forceinline__ float fast_sigmoid(float x) { return __builtin_amdgcn_rcpf(1.0f + __builtin_amdgcn_exp2f(-1.4426950408889634f * x)); }
;     __device__ __forceinline__ void operator()(const f32x4 (&acc)[2][2][4][2], const Unit& u, int wr, int wc, int fr, int fq) const {
;     ...
; #pragma unroll
;         for (int ai = 0; ai < 2; ++ai)
; #pragma unroll
;             for (int m = 0; m < 4; ++m) { bf16_t* rowp = base + (size_t)(row0 + ai * HALF + m * 16) * ldc + col0;
;                 const float rs = rsq[ai][m];
; #pragma unroll
;                 for (int bj = 0; bj < 2; ++bj) { f32x4 v0 = acc[ai][bj][m][0] * rs + bv[bj][0], v1 = acc[ai][bj][m][1] * rs + bv[bj][1];
;                     if (isg) {
; #pragma unroll
;                         for (int e = 0; e < 4; ++e) { v0[e] = fast_sigmoid(v0[e]); v1[e] = fast_sigmoid(v1[e]); } }
;                     u32x4 w; w.x = cvt_pk_bf16(v0[0], v0[1]); w.y = cvt_pk_bf16(v0[2], v0[3]); w.z = cvt_pk_bf16(v1[0], v1[1]); w.w = cvt_pk_bf16(v1[2], v1[3]);
;                     *(u32x4*)(rowp + bj * HALF) = w; } }
.LBB0_258:
	s_and_b64 s[12:13], s[52:53], exec
	v_readlane_b32 s12, v252, 39
	s_cselect_b32 s12, s78, s12
	v_readlane_b32 s13, v252, 38
	s_cselect_b32 s13, s35, s13
	v_mov_b32_e32 v123, s12
	s_movk_i32 s12, 0x1500
	v_mov_b32_e32 v122, s13
	s_cselect_b32 s12, 0xc00, s12
	v_lshl_add_u64 v[122:123], v[164:165], 1, v[122:123]
	v_mad_i64_i32 v[124:125], s[24:25], s12, v146, 0
	v_lshl_add_u64 v[124:125], v[124:125], 1, v[122:123]
	v_cvt_pk_bf16_f32 v126, v126, v127
	v_cvt_pk_bf16_f32 v127, v128, v129
	v_mov_b32_e32 v167, v166
	v_cvt_pk_bf16_f32 v128, v170, v171
	v_cvt_pk_bf16_f32 v129, v168, v169
	flat_store_dwordx4 v[124:125], v[126:129] sc1 nt
	s_waitcnt lgkmcnt(0)
	v_pk_fma_f32 v[118:119], v[118:119], v[166:167], v[134:135]
	s_and_b64 vcc, exec, s[44:45]
	v_mov_b32_e32 v126, v166
	v_mov_b32_e32 v127, v166
	v_pk_fma_f32 v[120:121], v[120:121], v[126:127], v[136:137]
	v_pk_fma_f32 v[116:117], v[116:117], v[126:127], v[132:133]
	v_pk_fma_f32 v[114:115], v[114:115], v[166:167], v[130:131]
	s_cbranch_vccnz .LBB0_260
	v_mul_f32_e32 v0, 0xbfb8aa3b, v118
	v_exp_f32_e32 v0, v0
	v_mul_f32_e32 v115, 0xbfb8aa3b, v115
	v_exp_f32_e32 v115, v115
	v_mul_f32_e32 v114, 0xbfb8aa3b, v114
	v_add_f32_e32 v0, 1.0, v0
	v_rcp_f32_e32 v118, v0
	v_mul_f32_e32 v0, 0xbfb8aa3b, v119
	v_exp_f32_e32 v0, v0
	v_exp_f32_e32 v114, v114
	v_add_f32_e32 v0, 1.0, v0
	v_rcp_f32_e32 v119, v0
	v_add_f32_e32 v0, 1.0, v115
	v_mul_f32_e32 v115, 0xbfb8aa3b, v120
	v_exp_f32_e32 v120, v115
	v_mul_f32_e32 v115, 0xbfb8aa3b, v116
	v_exp_f32_e32 v116, v115
	v_rcp_f32_e32 v115, v0
	v_add_f32_e32 v0, 1.0, v120
	v_rcp_f32_e32 v120, v0
	v_add_f32_e32 v0, 1.0, v116
	v_mul_f32_e32 v116, 0xbfb8aa3b, v121
	v_exp_f32_e32 v121, v116
	v_mul_f32_e32 v116, 0xbfb8aa3b, v117
	v_exp_f32_e32 v117, v116
	v_rcp_f32_e32 v116, v0
	v_add_f32_e32 v0, 1.0, v121
	v_add_f32_e32 v114, 1.0, v114
	v_rcp_f32_e32 v121, v0
	v_add_f32_e32 v0, 1.0, v117
	v_rcp_f32_e32 v114, v114
	v_rcp_f32_e32 v117, v0
.LBB0_260:
	v_cvt_pk_bf16_f32 v118, v118, v119
	v_cvt_pk_bf16_f32 v119, v120, v121
	v_cvt_pk_bf16_f32 v120, v114, v115
	v_pk_fma_f32 v[112:113], v[112:113], v[162:163], v[144:145] op_sel_hi:[1,0,1]
	v_pk_fma_f32 v[110:111], v[110:111], v[162:163], v[142:143] op_sel_hi:[1,0,1]
	v_pk_fma_f32 v[108:109], v[108:109], v[162:163], v[140:141] op_sel_hi:[1,0,1]
	s_and_b64 vcc, exec, s[44:45]
	v_pk_fma_f32 v[114:115], v[106:107], v[162:163], v[138:139] op_sel_hi:[1,0,1]
	v_cvt_pk_bf16_f32 v121, v116, v117
	flat_store_dwordx4 v[124:125], v[118:121] offset:256 sc1 nt
	s_cbranch_vccnz .LBB0_262
	v_mul_f32_e32 v0, 0xbfb8aa3b, v110
	v_exp_f32_e32 v0, v0
	v_mul_f32_e32 v106, 0xbfb8aa3b, v114
	v_exp_f32_e32 v106, v106
	v_mul_f32_e32 v107, 0xbfb8aa3b, v115
	v_add_f32_e32 v0, 1.0, v0
	v_rcp_f32_e32 v110, v0
	v_mul_f32_e32 v0, 0xbfb8aa3b, v111
	v_exp_f32_e32 v0, v0
	v_exp_f32_e32 v107, v107
	v_add_f32_e32 v106, 1.0, v106
	v_rcp_f32_e32 v114, v106
	v_add_f32_e32 v0, 1.0, v0
	v_mul_f32_e32 v106, 0xbfb8aa3b, v112
	v_rcp_f32_e32 v111, v0
	v_add_f32_e32 v0, 1.0, v107
	v_exp_f32_e32 v106, v106
	v_mul_f32_e32 v107, 0xbfb8aa3b, v108
	v_exp_f32_e32 v107, v107
	v_rcp_f32_e32 v115, v0
	v_add_f32_e32 v0, 1.0, v106
	v_mul_f32_e32 v106, 0xbfb8aa3b, v113
	v_rcp_f32_e32 v112, v0
	v_add_f32_e32 v0, 1.0, v107
	v_exp_f32_e32 v106, v106
	v_mul_f32_e32 v107, 0xbfb8aa3b, v109
	v_exp_f32_e32 v107, v107
	v_rcp_f32_e32 v108, v0
	v_add_f32_e32 v0, 1.0, v106
	v_rcp_f32_e32 v113, v0
	v_add_f32_e32 v0, 1.0, v107
	v_rcp_f32_e32 v109, v0
.LBB0_262:
	v_or_b32_e32 v0, 16, v146
	v_mov_b32_e32 v163, v162
	v_mad_i64_i32 v[106:107], s[24:25], s12, v0, 0
	v_cvt_pk_bf16_f32 v110, v110, v111
	v_cvt_pk_bf16_f32 v111, v112, v113
	v_cvt_pk_bf16_f32 v112, v114, v115
	v_cvt_pk_bf16_f32 v113, v108, v109
	v_mov_b32_e32 v108, v162
	v_mov_b32_e32 v109, v162
	v_lshl_add_u64 v[106:107], v[106:107], 1, v[122:123]
	v_pk_fma_f32 v[104:105], v[104:105], v[108:109], v[136:137]
	v_pk_fma_f32 v[102:103], v[102:103], v[162:163], v[134:135]
	v_pk_fma_f32 v[100:101], v[100:101], v[108:109], v[132:133]
	s_and_b64 vcc, exec, s[44:45]
	v_pk_fma_f32 v[98:99], v[98:99], v[162:163], v[130:131]
	flat_store_dwordx4 v[106:107], v[110:113] sc1 nt
	s_cbranch_vccnz .LBB0_264
	v_mul_f32_e32 v0, 0xbfb8aa3b, v102
	v_exp_f32_e32 v0, v0
	v_mul_f32_e32 v99, 0xbfb8aa3b, v99
	v_exp_f32_e32 v99, v99
	v_mul_f32_e32 v98, 0xbfb8aa3b, v98
	v_add_f32_e32 v0, 1.0, v0
	v_rcp_f32_e32 v102, v0
	v_mul_f32_e32 v0, 0xbfb8aa3b, v103
	v_exp_f32_e32 v0, v0
	v_exp_f32_e32 v98, v98
	v_add_f32_e32 v0, 1.0, v0
	v_rcp_f32_e32 v103, v0
	v_add_f32_e32 v0, 1.0, v99
	v_mul_f32_e32 v99, 0xbfb8aa3b, v104
	v_exp_f32_e32 v104, v99
	v_mul_f32_e32 v99, 0xbfb8aa3b, v100
	v_exp_f32_e32 v100, v99
	v_rcp_f32_e32 v99, v0
	v_add_f32_e32 v0, 1.0, v104
	v_rcp_f32_e32 v104, v0
	v_add_f32_e32 v0, 1.0, v100
	v_mul_f32_e32 v100, 0xbfb8aa3b, v105
	v_exp_f32_e32 v105, v100
	v_mul_f32_e32 v100, 0xbfb8aa3b, v101
	v_exp_f32_e32 v101, v100
	v_rcp_f32_e32 v100, v0
	v_add_f32_e32 v0, 1.0, v105
	v_add_f32_e32 v98, 1.0, v98
	v_rcp_f32_e32 v105, v0
	v_add_f32_e32 v0, 1.0, v101
	v_rcp_f32_e32 v98, v98
	v_rcp_f32_e32 v101, v0
; __device__ __forceinline__ unsigned cvt_pk_bf16(float lo, float hi) { unsigned r; asm volatile("v_cvt_pk_bf16_f32 %0, %1, %2" : "=v"(r) : "v"(lo), "v"(hi)); return r; }
; __device__ __forceinline__ float fast_sigmoid(float x) { return __builtin_amdgcn_rcpf(1.0f + __builtin_amdgcn_exp2f(-1.4426950408889634f * x)); }
;     __device__ __forceinline__ void operator()(const f32x4 (&acc)[2][2][4][2], const Unit& u, int wr, int wc, int fr, int fq) const {
;     ...
; #pragma unroll
;         for (int ai = 0; ai < 2; ++ai)
; #pragma unroll
;             for (int m = 0; m < 4; ++m) { bf16_t* rowp = base + (size_t)(row0 + ai * HALF + m * 16) * ldc + col0;
;                 const float rs = rsq[ai][m];
; #pragma unroll
;                 for (int bj = 0; bj < 2; ++bj) { f32x4 v0 = acc[ai][bj][m][0] * rs + bv[bj][0], v1 = acc[ai][bj][m][1] * rs + bv[bj][1];
;                     if (isg) {
; #pragma unroll
;                         for (int e = 0; e < 4; ++e) { v0[e] = fast_sigmoid(v0[e]); v1[e] = fast_sigmoid(v1[e]); } }
;                     u32x4 w; w.x = cvt_pk_bf16(v0[0], v0[1]); w.y = cvt_pk_bf16(v0[2], v0[3]); w.z = cvt_pk_bf16(v1[0], v1[1]); w.w = cvt_pk_bf16(v1[2], v1[3]);
;                     *(u32x4*)(rowp + bj * HALF) = w; } }
.LBB0_264:
	v_cvt_pk_bf16_f32 v102, v102, v103
	v_cvt_pk_bf16_f32 v103, v104, v105
	v_cvt_pk_bf16_f32 v104, v98, v99
	v_pk_fma_f32 v[96:97], v[96:97], v[160:161], v[144:145] op_sel_hi:[1,0,1]
	v_pk_fma_f32 v[94:95], v[94:95], v[160:161], v[142:143] op_sel_hi:[1,0,1]
	v_pk_fma_f32 v[92:93], v[92:93], v[160:161], v[140:141] op_sel_hi:[1,0,1]
	s_and_b64 vcc, exec, s[44:45]
	v_pk_fma_f32 v[98:99], v[90:91], v[160:161], v[138:139] op_sel_hi:[1,0,1]
	v_cvt_pk_bf16_f32 v105, v100, v101
	flat_store_dwordx4 v[106:107], v[102:105] offset:256 sc1 nt
	s_cbranch_vccnz .LBB0_266
	v_mul_f32_e32 v0, 0xbfb8aa3b, v94
	v_exp_f32_e32 v0, v0
	v_mul_f32_e32 v90, 0xbfb8aa3b, v98
	v_exp_f32_e32 v90, v90
	v_mul_f32_e32 v91, 0xbfb8aa3b, v99
	v_add_f32_e32 v0, 1.0, v0
	v_rcp_f32_e32 v94, v0
	v_mul_f32_e32 v0, 0xbfb8aa3b, v95
	v_exp_f32_e32 v0, v0
	v_exp_f32_e32 v91, v91
	v_add_f32_e32 v90, 1.0, v90
	v_rcp_f32_e32 v98, v90
	v_add_f32_e32 v0, 1.0, v0
	v_mul_f32_e32 v90, 0xbfb8aa3b, v96
	v_rcp_f32_e32 v95, v0
	v_add_f32_e32 v0, 1.0, v91
	v_exp_f32_e32 v90, v90
	v_mul_f32_e32 v91, 0xbfb8aa3b, v92
	v_exp_f32_e32 v91, v91
	v_rcp_f32_e32 v99, v0
	v_add_f32_e32 v0, 1.0, v90
	v_mul_f32_e32 v90, 0xbfb8aa3b, v97
	v_rcp_f32_e32 v96, v0
	v_add_f32_e32 v0, 1.0, v91
	v_exp_f32_e32 v90, v90
	v_mul_f32_e32 v91, 0xbfb8aa3b, v93
	v_exp_f32_e32 v91, v91
	v_rcp_f32_e32 v92, v0
	v_add_f32_e32 v0, 1.0, v90
	v_rcp_f32_e32 v97, v0
	v_add_f32_e32 v0, 1.0, v91
	v_rcp_f32_e32 v93, v0
.LBB0_266:
	v_or_b32_e32 v0, 32, v146
	v_mov_b32_e32 v161, v160
	v_mad_i64_i32 v[90:91], s[24:25], s12, v0, 0
	v_cvt_pk_bf16_f32 v94, v94, v95
	v_cvt_pk_bf16_f32 v95, v96, v97
	v_cvt_pk_bf16_f32 v96, v98, v99
	v_cvt_pk_bf16_f32 v97, v92, v93
	v_mov_b32_e32 v92, v160
	v_mov_b32_e32 v93, v160
	v_lshl_add_u64 v[90:91], v[90:91], 1, v[122:123]
	v_pk_fma_f32 v[88:89], v[88:89], v[92:93], v[136:137]
	v_pk_fma_f32 v[86:87], v[86:87], v[160:161], v[134:135]
	v_pk_fma_f32 v[84:85], v[84:85], v[92:93], v[132:133]
	s_and_b64 vcc, exec, s[44:45]
	v_pk_fma_f32 v[82:83], v[82:83], v[160:161], v[130:131]
	flat_store_dwordx4 v[90:91], v[94:97] sc1 nt
	s_cbranch_vccnz .LBB0_268
	v_mul_f32_e32 v0, 0xbfb8aa3b, v86
	v_exp_f32_e32 v0, v0
	v_mul_f32_e32 v83, 0xbfb8aa3b, v83
	v_exp_f32_e32 v83, v83
	v_mul_f32_e32 v82, 0xbfb8aa3b, v82
	v_add_f32_e32 v0, 1.0, v0
	v_rcp_f32_e32 v86, v0
	v_mul_f32_e32 v0, 0xbfb8aa3b, v87
	v_exp_f32_e32 v0, v0
	v_exp_f32_e32 v82, v82
	v_add_f32_e32 v0, 1.0, v0
	v_rcp_f32_e32 v87, v0
	v_add_f32_e32 v0, 1.0, v83
	v_mul_f32_e32 v83, 0xbfb8aa3b, v88
	v_exp_f32_e32 v88, v83
	v_mul_f32_e32 v83, 0xbfb8aa3b, v84
	v_exp_f32_e32 v84, v83
	v_rcp_f32_e32 v83, v0
	v_add_f32_e32 v0, 1.0, v88
	v_rcp_f32_e32 v88, v0
	v_add_f32_e32 v0, 1.0, v84
	v_mul_f32_e32 v84, 0xbfb8aa3b, v89
	v_exp_f32_e32 v89, v84
	v_mul_f32_e32 v84, 0xbfb8aa3b, v85
	v_exp_f32_e32 v85, v84
	v_rcp_f32_e32 v84, v0
	v_add_f32_e32 v0, 1.0, v89
	v_add_f32_e32 v82, 1.0, v82
	v_rcp_f32_e32 v89, v0
	v_add_f32_e32 v0, 1.0, v85
	v_rcp_f32_e32 v82, v82
	v_rcp_f32_e32 v85, v0
.LBB0_268:
	v_cvt_pk_bf16_f32 v86, v86, v87
	v_cvt_pk_bf16_f32 v87, v88, v89
	v_cvt_pk_bf16_f32 v88, v82, v83
	v_pk_fma_f32 v[80:81], v[80:81], v[158:159], v[144:145] op_sel_hi:[1,0,1]
	v_pk_fma_f32 v[78:79], v[78:79], v[158:159], v[142:143] op_sel_hi:[1,0,1]
	v_pk_fma_f32 v[76:77], v[76:77], v[158:159], v[140:141] op_sel_hi:[1,0,1]
	s_and_b64 vcc, exec, s[44:45]
	v_pk_fma_f32 v[82:83], v[74:75], v[158:159], v[138:139] op_sel_hi:[1,0,1]
	v_cvt_pk_bf16_f32 v89, v84, v85
	flat_store_dwordx4 v[90:91], v[86:89] offset:256 sc1 nt
	s_cbranch_vccnz .LBB0_270
	v_mul_f32_e32 v0, 0xbfb8aa3b, v78
	v_exp_f32_e32 v0, v0
	v_mul_f32_e32 v74, 0xbfb8aa3b, v82
	v_exp_f32_e32 v74, v74
	v_mul_f32_e32 v75, 0xbfb8aa3b, v83
	v_add_f32_e32 v0, 1.0, v0
	v_rcp_f32_e32 v78, v0
	v_mul_f32_e32 v0, 0xbfb8aa3b, v79
	v_exp_f32_e32 v0, v0
	v_exp_f32_e32 v75, v75
	v_add_f32_e32 v74, 1.0, v74
	v_rcp_f32_e32 v82, v74
	v_add_f32_e32 v0, 1.0, v0
	v_mul_f32_e32 v74, 0xbfb8aa3b, v80
	v_rcp_f32_e32 v79, v0
	v_add_f32_e32 v0, 1.0, v75
	v_exp_f32_e32 v74, v74
	v_mul_f32_e32 v75, 0xbfb8aa3b, v76
	v_exp_f32_e32 v75, v75
	v_rcp_f32_e32 v83, v0
	v_add_f32_e32 v0, 1.0, v74
	v_mul_f32_e32 v74, 0xbfb8aa3b, v81
	v_rcp_f32_e32 v80, v0
	v_add_f32_e32 v0, 1.0, v75
	v_exp_f32_e32 v74, v74
	v_mul_f32_e32 v75, 0xbfb8aa3b, v77
	v_exp_f32_e32 v75, v75
	v_rcp_f32_e32 v76, v0
	v_add_f32_e32 v0, 1.0, v74
	v_rcp_f32_e32 v81, v0
	v_add_f32_e32 v0, 1.0, v75
	v_rcp_f32_e32 v77, v0
.LBB0_270:
	v_or_b32_e32 v0, 48, v146
	v_mov_b32_e32 v159, v158
	v_mad_i64_i32 v[74:75], s[24:25], s12, v0, 0
	v_cvt_pk_bf16_f32 v78, v78, v79
	v_cvt_pk_bf16_f32 v79, v80, v81
	v_cvt_pk_bf16_f32 v80, v82, v83
	v_cvt_pk_bf16_f32 v81, v76, v77
	v_mov_b32_e32 v76, v158
	v_mov_b32_e32 v77, v158
	v_lshl_add_u64 v[74:75], v[74:75], 1, v[122:123]
	v_pk_fma_f32 v[72:73], v[72:73], v[76:77], v[136:137]
	v_pk_fma_f32 v[70:71], v[70:71], v[158:159], v[134:135]
	v_pk_fma_f32 v[68:69], v[68:69], v[76:77], v[132:133]
	s_and_b64 vcc, exec, s[44:45]
	v_pk_fma_f32 v[66:67], v[66:67], v[158:159], v[130:131]
	flat_store_dwordx4 v[74:75], v[78:81] sc1 nt
	s_cbranch_vccnz .LBB0_272
	v_mul_f32_e32 v0, 0xbfb8aa3b, v70
	v_exp_f32_e32 v0, v0
	v_mul_f32_e32 v67, 0xbfb8aa3b, v67
	v_exp_f32_e32 v67, v67
	v_mul_f32_e32 v66, 0xbfb8aa3b, v66
	v_add_f32_e32 v0, 1.0, v0
	v_rcp_f32_e32 v70, v0
	v_mul_f32_e32 v0, 0xbfb8aa3b, v71
	v_exp_f32_e32 v0, v0
	v_exp_f32_e32 v66, v66
	v_add_f32_e32 v0, 1.0, v0
	v_rcp_f32_e32 v71, v0
	v_add_f32_e32 v0, 1.0, v67
	v_mul_f32_e32 v67, 0xbfb8aa3b, v72
	v_exp_f32_e32 v72, v67
	v_mul_f32_e32 v67, 0xbfb8aa3b, v68
	v_exp_f32_e32 v68, v67
	v_rcp_f32_e32 v67, v0
	v_add_f32_e32 v0, 1.0, v72
	v_rcp_f32_e32 v72, v0
	v_add_f32_e32 v0, 1.0, v68
	v_mul_f32_e32 v68, 0xbfb8aa3b, v73
	v_exp_f32_e32 v73, v68
	v_mul_f32_e32 v68, 0xbfb8aa3b, v69
	v_exp_f32_e32 v69, v68
	v_rcp_f32_e32 v68, v0
	v_add_f32_e32 v0, 1.0, v73
	v_add_f32_e32 v66, 1.0, v66
	v_rcp_f32_e32 v73, v0
	v_add_f32_e32 v0, 1.0, v69
	v_rcp_f32_e32 v66, v66
	v_rcp_f32_e32 v69, v0
; __device__ __forceinline__ unsigned cvt_pk_bf16(float lo, float hi) { unsigned r; asm volatile("v_cvt_pk_bf16_f32 %0, %1, %2" : "=v"(r) : "v"(lo), "v"(hi)); return r; }
; __device__ __forceinline__ float fast_sigmoid(float x) { return __builtin_amdgcn_rcpf(1.0f + __builtin_amdgcn_exp2f(-1.4426950408889634f * x)); }
;     __device__ __forceinline__ void operator()(const f32x4 (&acc)[2][2][4][2], const Unit& u, int wr, int wc, int fr, int fq) const {
;     ...
; #pragma unroll
;         for (int ai = 0; ai < 2; ++ai)
; #pragma unroll
;             for (int m = 0; m < 4; ++m) { bf16_t* rowp = base + (size_t)(row0 + ai * HALF + m * 16) * ldc + col0;
;                 const float rs = rsq[ai][m];
; #pragma unroll
;                 for (int bj = 0; bj < 2; ++bj) { f32x4 v0 = acc[ai][bj][m][0] * rs + bv[bj][0], v1 = acc[ai][bj][m][1] * rs + bv[bj][1];
;                     if (isg) {
; #pragma unroll
;                         for (int e = 0; e < 4; ++e) { v0[e] = fast_sigmoid(v0[e]); v1[e] = fast_sigmoid(v1[e]); } }
;                     u32x4 w; w.x = cvt_pk_bf16(v0[0], v0[1]); w.y = cvt_pk_bf16(v0[2], v0[3]); w.z = cvt_pk_bf16(v1[0], v1[1]); w.w = cvt_pk_bf16(v1[2], v1[3]);
;                     *(u32x4*)(rowp + bj * HALF) = w; } }
.LBB0_272:
	v_cvt_pk_bf16_f32 v70, v70, v71
	v_cvt_pk_bf16_f32 v71, v72, v73
	v_cvt_pk_bf16_f32 v72, v66, v67
	v_pk_fma_f32 v[64:65], v[64:65], v[154:155], v[144:145] op_sel_hi:[1,0,1]
	v_pk_fma_f32 v[62:63], v[62:63], v[154:155], v[142:143] op_sel_hi:[1,0,1]
	v_pk_fma_f32 v[60:61], v[60:61], v[154:155], v[140:141] op_sel_hi:[1,0,1]
	s_and_b64 vcc, exec, s[44:45]
	v_pk_fma_f32 v[66:67], v[58:59], v[154:155], v[138:139] op_sel_hi:[1,0,1]
	v_cvt_pk_bf16_f32 v73, v68, v69
	flat_store_dwordx4 v[74:75], v[70:73] offset:256 sc1 nt
	s_cbranch_vccnz .LBB0_274
	v_mul_f32_e32 v0, 0xbfb8aa3b, v62
	v_exp_f32_e32 v0, v0
	v_mul_f32_e32 v58, 0xbfb8aa3b, v66
	v_exp_f32_e32 v58, v58
	v_mul_f32_e32 v59, 0xbfb8aa3b, v67
	v_add_f32_e32 v0, 1.0, v0
	v_rcp_f32_e32 v62, v0
	v_mul_f32_e32 v0, 0xbfb8aa3b, v63
	v_exp_f32_e32 v0, v0
	v_exp_f32_e32 v59, v59
	v_add_f32_e32 v58, 1.0, v58
	v_rcp_f32_e32 v66, v58
	v_add_f32_e32 v0, 1.0, v0
	v_mul_f32_e32 v58, 0xbfb8aa3b, v64
	v_rcp_f32_e32 v63, v0
	v_add_f32_e32 v0, 1.0, v59
	v_exp_f32_e32 v58, v58
	v_mul_f32_e32 v59, 0xbfb8aa3b, v60
	v_exp_f32_e32 v59, v59
	v_rcp_f32_e32 v67, v0
	v_add_f32_e32 v0, 1.0, v58
	v_mul_f32_e32 v58, 0xbfb8aa3b, v65
	v_rcp_f32_e32 v64, v0
	v_add_f32_e32 v0, 1.0, v59
	v_exp_f32_e32 v58, v58
	v_mul_f32_e32 v59, 0xbfb8aa3b, v61
	v_exp_f32_e32 v59, v59
	v_rcp_f32_e32 v60, v0
	v_add_f32_e32 v0, 1.0, v58
	v_rcp_f32_e32 v65, v0
	v_add_f32_e32 v0, 1.0, v59
	v_rcp_f32_e32 v61, v0
.LBB0_274:
	v_mov_b32_e32 v155, v154
	v_mad_i64_i32 v[58:59], s[24:25], s12, v156, 0
	v_cvt_pk_bf16_f32 v62, v62, v63
	v_cvt_pk_bf16_f32 v63, v64, v65
	v_cvt_pk_bf16_f32 v64, v66, v67
	v_cvt_pk_bf16_f32 v65, v60, v61
	v_mov_b32_e32 v60, v154
	v_mov_b32_e32 v61, v154
	v_lshl_add_u64 v[58:59], v[58:59], 1, v[122:123]
	v_pk_fma_f32 v[56:57], v[56:57], v[60:61], v[136:137]
	v_pk_fma_f32 v[54:55], v[54:55], v[154:155], v[134:135]
	v_pk_fma_f32 v[52:53], v[52:53], v[60:61], v[132:133]
	s_and_b64 vcc, exec, s[44:45]
	v_pk_fma_f32 v[50:51], v[50:51], v[154:155], v[130:131]
	flat_store_dwordx4 v[58:59], v[62:65] sc1 nt
	s_cbranch_vccnz .LBB0_276
	v_mul_f32_e32 v0, 0xbfb8aa3b, v54
	v_exp_f32_e32 v0, v0
	v_mul_f32_e32 v51, 0xbfb8aa3b, v51
	v_exp_f32_e32 v51, v51
	v_mul_f32_e32 v50, 0xbfb8aa3b, v50
	v_add_f32_e32 v0, 1.0, v0
	v_rcp_f32_e32 v54, v0
	v_mul_f32_e32 v0, 0xbfb8aa3b, v55
	v_exp_f32_e32 v0, v0
	v_exp_f32_e32 v50, v50
	v_add_f32_e32 v0, 1.0, v0
	v_rcp_f32_e32 v55, v0
	v_add_f32_e32 v0, 1.0, v51
	v_mul_f32_e32 v51, 0xbfb8aa3b, v56
	v_exp_f32_e32 v56, v51
	v_mul_f32_e32 v51, 0xbfb8aa3b, v52
	v_exp_f32_e32 v52, v51
	v_rcp_f32_e32 v51, v0
	v_add_f32_e32 v0, 1.0, v56
	v_rcp_f32_e32 v56, v0
	v_add_f32_e32 v0, 1.0, v52
	v_mul_f32_e32 v52, 0xbfb8aa3b, v57
	v_exp_f32_e32 v57, v52
	v_mul_f32_e32 v52, 0xbfb8aa3b, v53
	v_exp_f32_e32 v53, v52
	v_rcp_f32_e32 v52, v0
	v_add_f32_e32 v0, 1.0, v57
	v_add_f32_e32 v50, 1.0, v50
	v_rcp_f32_e32 v57, v0
	v_add_f32_e32 v0, 1.0, v53
	v_rcp_f32_e32 v50, v50
	v_rcp_f32_e32 v53, v0
.LBB0_276:
	v_cvt_pk_bf16_f32 v54, v54, v55
	v_cvt_pk_bf16_f32 v55, v56, v57
	v_cvt_pk_bf16_f32 v56, v50, v51
	v_pk_fma_f32 v[48:49], v[48:49], v[152:153], v[144:145] op_sel_hi:[1,0,1]
	v_pk_fma_f32 v[46:47], v[46:47], v[152:153], v[142:143] op_sel_hi:[1,0,1]
	v_pk_fma_f32 v[44:45], v[44:45], v[152:153], v[140:141] op_sel_hi:[1,0,1]
	s_and_b64 vcc, exec, s[44:45]
	v_pk_fma_f32 v[50:51], v[42:43], v[152:153], v[138:139] op_sel_hi:[1,0,1]
	v_cvt_pk_bf16_f32 v57, v52, v53
	flat_store_dwordx4 v[58:59], v[54:57] offset:256 sc1 nt
	s_cbranch_vccnz .LBB0_278
	v_mul_f32_e32 v0, 0xbfb8aa3b, v46
	v_exp_f32_e32 v0, v0
	v_mul_f32_e32 v42, 0xbfb8aa3b, v50
	v_exp_f32_e32 v42, v42
	v_mul_f32_e32 v43, 0xbfb8aa3b, v51
	v_add_f32_e32 v0, 1.0, v0
	v_rcp_f32_e32 v46, v0
	v_mul_f32_e32 v0, 0xbfb8aa3b, v47
	v_exp_f32_e32 v0, v0
	v_exp_f32_e32 v43, v43
	v_add_f32_e32 v42, 1.0, v42
	v_rcp_f32_e32 v50, v42
	v_add_f32_e32 v0, 1.0, v0
	v_mul_f32_e32 v42, 0xbfb8aa3b, v48
	v_rcp_f32_e32 v47, v0
	v_add_f32_e32 v0, 1.0, v43
	v_exp_f32_e32 v42, v42
	v_mul_f32_e32 v43, 0xbfb8aa3b, v44
	v_exp_f32_e32 v43, v43
	v_rcp_f32_e32 v51, v0
	v_add_f32_e32 v0, 1.0, v42
	v_mul_f32_e32 v42, 0xbfb8aa3b, v49
	v_rcp_f32_e32 v48, v0
	v_add_f32_e32 v0, 1.0, v43
	v_exp_f32_e32 v42, v42
	v_mul_f32_e32 v43, 0xbfb8aa3b, v45
	v_exp_f32_e32 v43, v43
	v_rcp_f32_e32 v44, v0
	v_add_f32_e32 v0, 1.0, v42
	v_rcp_f32_e32 v49, v0
	v_add_f32_e32 v0, 1.0, v43
	v_rcp_f32_e32 v45, v0
.LBB0_278:
	v_add_u32_e32 v0, 0x90, v146
	v_mov_b32_e32 v153, v152
	v_mad_i64_i32 v[42:43], s[24:25], s12, v0, 0
	v_cvt_pk_bf16_f32 v46, v46, v47
	v_cvt_pk_bf16_f32 v47, v48, v49
	v_cvt_pk_bf16_f32 v48, v50, v51
	v_cvt_pk_bf16_f32 v49, v44, v45
	v_mov_b32_e32 v44, v152
	v_mov_b32_e32 v45, v152
	v_lshl_add_u64 v[42:43], v[42:43], 1, v[122:123]
	v_pk_fma_f32 v[40:41], v[40:41], v[44:45], v[136:137]
	v_pk_fma_f32 v[38:39], v[38:39], v[152:153], v[134:135]
	v_pk_fma_f32 v[36:37], v[36:37], v[44:45], v[132:133]
	s_and_b64 vcc, exec, s[44:45]
	v_pk_fma_f32 v[34:35], v[34:35], v[152:153], v[130:131]
	flat_store_dwordx4 v[42:43], v[46:49] sc1 nt
	s_cbranch_vccnz .LBB0_280
	v_mul_f32_e32 v0, 0xbfb8aa3b, v38
	v_exp_f32_e32 v0, v0
	v_mul_f32_e32 v35, 0xbfb8aa3b, v35
	v_exp_f32_e32 v35, v35
	v_mul_f32_e32 v34, 0xbfb8aa3b, v34
	v_add_f32_e32 v0, 1.0, v0
	v_rcp_f32_e32 v38, v0
	v_mul_f32_e32 v0, 0xbfb8aa3b, v39
	v_exp_f32_e32 v0, v0
	v_exp_f32_e32 v34, v34
	v_add_f32_e32 v0, 1.0, v0
	v_rcp_f32_e32 v39, v0
	v_add_f32_e32 v0, 1.0, v35
	v_mul_f32_e32 v35, 0xbfb8aa3b, v40
	v_exp_f32_e32 v40, v35
	v_mul_f32_e32 v35, 0xbfb8aa3b, v36
	v_exp_f32_e32 v36, v35
	v_rcp_f32_e32 v35, v0
	v_add_f32_e32 v0, 1.0, v40
	v_rcp_f32_e32 v40, v0
	v_add_f32_e32 v0, 1.0, v36
	v_mul_f32_e32 v36, 0xbfb8aa3b, v41
	v_exp_f32_e32 v41, v36
	v_mul_f32_e32 v36, 0xbfb8aa3b, v37
	v_exp_f32_e32 v37, v36
	v_rcp_f32_e32 v36, v0
	v_add_f32_e32 v0, 1.0, v41
	v_add_f32_e32 v34, 1.0, v34
	v_rcp_f32_e32 v41, v0
	v_add_f32_e32 v0, 1.0, v37
	v_rcp_f32_e32 v34, v34
	v_rcp_f32_e32 v37, v0
; __device__ __forceinline__ unsigned cvt_pk_bf16(float lo, float hi) { unsigned r; asm volatile("v_cvt_pk_bf16_f32 %0, %1, %2" : "=v"(r) : "v"(lo), "v"(hi)); return r; }
; __device__ __forceinline__ float fast_sigmoid(float x) { return __builtin_amdgcn_rcpf(1.0f + __builtin_amdgcn_exp2f(-1.4426950408889634f * x)); }
;     __device__ __forceinline__ void operator()(const f32x4 (&acc)[2][2][4][2], const Unit& u, int wr, int wc, int fr, int fq) const {
;     ...
; #pragma unroll
;         for (int ai = 0; ai < 2; ++ai)
; #pragma unroll
;             for (int m = 0; m < 4; ++m) { bf16_t* rowp = base + (size_t)(row0 + ai * HALF + m * 16) * ldc + col0;
;                 const float rs = rsq[ai][m];
; #pragma unroll
;                 for (int bj = 0; bj < 2; ++bj) { f32x4 v0 = acc[ai][bj][m][0] * rs + bv[bj][0], v1 = acc[ai][bj][m][1] * rs + bv[bj][1];
;                     if (isg) {
; #pragma unroll
;                         for (int e = 0; e < 4; ++e) { v0[e] = fast_sigmoid(v0[e]); v1[e] = fast_sigmoid(v1[e]); } }
;                     u32x4 w; w.x = cvt_pk_bf16(v0[0], v0[1]); w.y = cvt_pk_bf16(v0[2], v0[3]); w.z = cvt_pk_bf16(v1[0], v1[1]); w.w = cvt_pk_bf16(v1[2], v1[3]);
;                     *(u32x4*)(rowp + bj * HALF) = w; } }
.LBB0_280:
	v_cvt_pk_bf16_f32 v38, v38, v39
	v_cvt_pk_bf16_f32 v39, v40, v41
	v_cvt_pk_bf16_f32 v40, v34, v35
	v_pk_fma_f32 v[32:33], v[32:33], v[150:151], v[144:145] op_sel_hi:[1,0,1]
	v_pk_fma_f32 v[30:31], v[30:31], v[150:151], v[142:143] op_sel_hi:[1,0,1]
	v_pk_fma_f32 v[28:29], v[28:29], v[150:151], v[140:141] op_sel_hi:[1,0,1]
	s_and_b64 vcc, exec, s[44:45]
	v_pk_fma_f32 v[34:35], v[26:27], v[150:151], v[138:139] op_sel_hi:[1,0,1]
	v_cvt_pk_bf16_f32 v41, v36, v37
	flat_store_dwordx4 v[42:43], v[38:41] offset:256 sc1 nt
	s_cbranch_vccnz .LBB0_282
	v_mul_f32_e32 v0, 0xbfb8aa3b, v30
	v_exp_f32_e32 v0, v0
	v_mul_f32_e32 v26, 0xbfb8aa3b, v34
	v_exp_f32_e32 v26, v26
	v_mul_f32_e32 v27, 0xbfb8aa3b, v35
	v_add_f32_e32 v0, 1.0, v0
	v_rcp_f32_e32 v30, v0
	v_mul_f32_e32 v0, 0xbfb8aa3b, v31
	v_exp_f32_e32 v0, v0
	v_exp_f32_e32 v27, v27
	v_add_f32_e32 v26, 1.0, v26
	v_rcp_f32_e32 v34, v26
	v_add_f32_e32 v0, 1.0, v0
	v_mul_f32_e32 v26, 0xbfb8aa3b, v32
	v_rcp_f32_e32 v31, v0
	v_add_f32_e32 v0, 1.0, v27
	v_exp_f32_e32 v26, v26
	v_mul_f32_e32 v27, 0xbfb8aa3b, v28
	v_exp_f32_e32 v27, v27
	v_rcp_f32_e32 v35, v0
	v_add_f32_e32 v0, 1.0, v26
	v_mul_f32_e32 v26, 0xbfb8aa3b, v33
	v_rcp_f32_e32 v32, v0
	v_add_f32_e32 v0, 1.0, v27
	v_exp_f32_e32 v26, v26
	v_mul_f32_e32 v27, 0xbfb8aa3b, v29
	v_exp_f32_e32 v27, v27
	v_rcp_f32_e32 v28, v0
	v_add_f32_e32 v0, 1.0, v26
	v_rcp_f32_e32 v33, v0
	v_add_f32_e32 v0, 1.0, v27
	v_rcp_f32_e32 v29, v0
.LBB0_282:
	v_add_u32_e32 v0, 0xa0, v146
	v_mov_b32_e32 v151, v150
	v_mad_i64_i32 v[26:27], s[24:25], s12, v0, 0
	v_cvt_pk_bf16_f32 v30, v30, v31
	v_cvt_pk_bf16_f32 v31, v32, v33
	v_cvt_pk_bf16_f32 v32, v34, v35
	v_cvt_pk_bf16_f32 v33, v28, v29
	v_mov_b32_e32 v28, v150
	v_mov_b32_e32 v29, v150
	v_lshl_add_u64 v[26:27], v[26:27], 1, v[122:123]
	v_pk_fma_f32 v[24:25], v[24:25], v[28:29], v[136:137]
	v_pk_fma_f32 v[22:23], v[22:23], v[150:151], v[134:135]
	v_pk_fma_f32 v[20:21], v[20:21], v[28:29], v[132:133]
	s_and_b64 vcc, exec, s[44:45]
	v_pk_fma_f32 v[18:19], v[18:19], v[150:151], v[130:131]
	flat_store_dwordx4 v[26:27], v[30:33] sc1 nt
	s_cbranch_vccnz .LBB0_284
	v_mul_f32_e32 v0, 0xbfb8aa3b, v22
	v_exp_f32_e32 v0, v0
	v_mul_f32_e32 v19, 0xbfb8aa3b, v19
	v_exp_f32_e32 v19, v19
	v_mul_f32_e32 v18, 0xbfb8aa3b, v18
	v_add_f32_e32 v0, 1.0, v0
	v_rcp_f32_e32 v22, v0
	v_mul_f32_e32 v0, 0xbfb8aa3b, v23
	v_exp_f32_e32 v0, v0
	v_exp_f32_e32 v18, v18
	v_add_f32_e32 v0, 1.0, v0
	v_rcp_f32_e32 v23, v0
	v_add_f32_e32 v0, 1.0, v19
	v_mul_f32_e32 v19, 0xbfb8aa3b, v24
	v_exp_f32_e32 v24, v19
	v_mul_f32_e32 v19, 0xbfb8aa3b, v20
	v_exp_f32_e32 v20, v19
	v_rcp_f32_e32 v19, v0
	v_add_f32_e32 v0, 1.0, v24
	v_rcp_f32_e32 v24, v0
	v_add_f32_e32 v0, 1.0, v20
	v_mul_f32_e32 v20, 0xbfb8aa3b, v25
	v_exp_f32_e32 v25, v20
	v_mul_f32_e32 v20, 0xbfb8aa3b, v21
	v_exp_f32_e32 v21, v20
	v_rcp_f32_e32 v20, v0
	v_add_f32_e32 v0, 1.0, v25
	v_add_f32_e32 v18, 1.0, v18
	v_rcp_f32_e32 v25, v0
	v_add_f32_e32 v0, 1.0, v21
	v_rcp_f32_e32 v18, v18
	v_rcp_f32_e32 v21, v0
.LBB0_284:
	v_cvt_pk_bf16_f32 v22, v22, v23
	v_cvt_pk_bf16_f32 v23, v24, v25
	v_cvt_pk_bf16_f32 v24, v18, v19
	v_pk_fma_f32 v[16:17], v[16:17], v[148:149], v[144:145] op_sel_hi:[1,0,1]
	v_pk_fma_f32 v[14:15], v[14:15], v[148:149], v[142:143] op_sel_hi:[1,0,1]
	v_pk_fma_f32 v[12:13], v[12:13], v[148:149], v[140:141] op_sel_hi:[1,0,1]
	s_and_b64 vcc, exec, s[44:45]
	v_pk_fma_f32 v[18:19], v[10:11], v[148:149], v[138:139] op_sel_hi:[1,0,1]
	v_cvt_pk_bf16_f32 v25, v20, v21
	flat_store_dwordx4 v[26:27], v[22:25] offset:256 sc1 nt
	s_cbranch_vccnz .LBB0_286
	v_mul_f32_e32 v0, 0xbfb8aa3b, v14
	v_exp_f32_e32 v0, v0
	v_mul_f32_e32 v10, 0xbfb8aa3b, v18
	v_exp_f32_e32 v10, v10
	v_mul_f32_e32 v11, 0xbfb8aa3b, v19
	v_add_f32_e32 v0, 1.0, v0
	v_rcp_f32_e32 v14, v0
	v_mul_f32_e32 v0, 0xbfb8aa3b, v15
	v_exp_f32_e32 v0, v0
	v_exp_f32_e32 v11, v11
	v_add_f32_e32 v10, 1.0, v10
	v_rcp_f32_e32 v18, v10
	v_add_f32_e32 v0, 1.0, v0
	v_mul_f32_e32 v10, 0xbfb8aa3b, v16
	v_rcp_f32_e32 v15, v0
	v_add_f32_e32 v0, 1.0, v11
	v_exp_f32_e32 v10, v10
	v_mul_f32_e32 v11, 0xbfb8aa3b, v12
	v_exp_f32_e32 v11, v11
	v_rcp_f32_e32 v19, v0
	v_add_f32_e32 v0, 1.0, v10
	v_mul_f32_e32 v10, 0xbfb8aa3b, v17
	v_rcp_f32_e32 v16, v0
	v_add_f32_e32 v0, 1.0, v11
	v_exp_f32_e32 v10, v10
	v_mul_f32_e32 v11, 0xbfb8aa3b, v13
	v_exp_f32_e32 v11, v11
	v_rcp_f32_e32 v12, v0
	v_add_f32_e32 v0, 1.0, v10
	v_rcp_f32_e32 v17, v0
	v_add_f32_e32 v0, 1.0, v11
	v_rcp_f32_e32 v13, v0
.LBB0_286:
	v_add_u32_e32 v0, 0xb0, v146
	v_mov_b32_e32 v149, v148
	v_mad_i64_i32 v[10:11], s[12:13], s12, v0, 0
	v_cvt_pk_bf16_f32 v14, v14, v15
	v_cvt_pk_bf16_f32 v15, v16, v17
	v_cvt_pk_bf16_f32 v16, v18, v19
	v_cvt_pk_bf16_f32 v17, v12, v13
	v_mov_b32_e32 v12, v148
	v_mov_b32_e32 v13, v148
	v_lshl_add_u64 v[10:11], v[10:11], 1, v[122:123]
	v_pk_fma_f32 v[8:9], v[8:9], v[12:13], v[136:137]
	v_pk_fma_f32 v[6:7], v[6:7], v[148:149], v[134:135]
	v_pk_fma_f32 v[4:5], v[4:5], v[12:13], v[132:133]
	s_and_b64 vcc, exec, s[44:45]
	v_pk_fma_f32 v[2:3], v[2:3], v[148:149], v[130:131]
	flat_store_dwordx4 v[10:11], v[14:17] sc1 nt
	s_cbranch_vccnz .LBB0_288
	v_mul_f32_e32 v0, 0xbfb8aa3b, v6
	v_exp_f32_e32 v0, v0
	v_mul_f32_e32 v3, 0xbfb8aa3b, v3
	v_exp_f32_e32 v3, v3
	v_mul_f32_e32 v2, 0xbfb8aa3b, v2
	v_add_f32_e32 v0, 1.0, v0
	v_rcp_f32_e32 v6, v0
	v_mul_f32_e32 v0, 0xbfb8aa3b, v7
	v_exp_f32_e32 v0, v0
	v_exp_f32_e32 v2, v2
	v_add_f32_e32 v0, 1.0, v0
	v_rcp_f32_e32 v7, v0
	v_add_f32_e32 v0, 1.0, v3
	v_mul_f32_e32 v3, 0xbfb8aa3b, v8
	v_exp_f32_e32 v8, v3
	v_mul_f32_e32 v3, 0xbfb8aa3b, v4
	v_exp_f32_e32 v4, v3
	v_rcp_f32_e32 v3, v0
	v_add_f32_e32 v0, 1.0, v8
	v_rcp_f32_e32 v8, v0
	v_add_f32_e32 v0, 1.0, v4
	v_mul_f32_e32 v4, 0xbfb8aa3b, v9
	v_exp_f32_e32 v9, v4
	v_mul_f32_e32 v4, 0xbfb8aa3b, v5
	v_exp_f32_e32 v5, v4
	v_rcp_f32_e32 v4, v0
	v_add_f32_e32 v0, 1.0, v9
	v_add_f32_e32 v2, 1.0, v2
	v_rcp_f32_e32 v9, v0
	v_add_f32_e32 v0, 1.0, v5
	v_rcp_f32_e32 v2, v2
	v_rcp_f32_e32 v5, v0
.LBB0_288:
	v_cvt_pk_bf16_f32 v6, v6, v7
	v_cvt_pk_bf16_f32 v7, v8, v9
	v_cvt_pk_bf16_f32 v8, v2, v3
	v_cvt_pk_bf16_f32 v9, v4, v5
	flat_store_dwordx4 v[10:11], v[6:9] offset:256 sc1 nt
	s_and_b64 vcc, exec, s[42:43]
	s_mov_b64 s[12:13], -1
	s_cbranch_vccnz .LBB0_124
